# attention g>0: previous-LSE dword requested before P.V (into v252) instead of loaded and waited for right after P.V
# baseline (speedup 1.0000x reference)
.LBB0_1166:
	s_and_b64 vcc, exec, s[44:45]
	s_cbranch_vccnz .LBB0_1168
	v_lshl_add_u64 v[0:1], s[18:19], 1, v[142:143]
	global_load_dwordx4 v[64:67], v[0:1], off
	v_lshlrev_b32_e32 v252, s40, v138
	v_add_u32_e32 v252, s47, v252
	v_lshlrev_b32_e32 v252, 4, v252
	v_add_u32_e32 v252, s46, v252
	v_lshlrev_b32_e32 v252, 2, v252
	global_load_dword v252, v252, s[22:23]
	s_branch .LBB0_1169

.LBB0_1177:
	v_cvt_pk_bf16_f32 v100, v100, v101
	v_cvt_pk_bf16_f32 v101, v102, v103
	v_cvt_pk_bf16_f32 v102, v104, v105
	v_cvt_pk_bf16_f32 v104, v108, v109
	v_cvt_pk_bf16_f32 v105, v110, v111
	ds_read_b128 v[108:111], v171 offset:256
	v_cvt_pk_bf16_f32 v103, v106, v107
	v_add_f32_e32 v117, v117, v118
	v_lshlrev_b32_e32 v118, s40, v138
	s_waitcnt lgkmcnt(0)
	v_mfma_f32_32x32x16_bf16 v[48:63], v[108:111], v[100:103], v[48:63]
	ds_read_b128 v[108:111], v171 offset:25344
	v_cvt_pk_bf16_f32 v106, v112, v113
	v_cvt_pk_bf16_f32 v107, v114, v116
	v_add_u32_e32 v112, s47, v118
	s_waitcnt lgkmcnt(0)
	v_mfma_f32_32x32x16_bf16 v[32:47], v[108:111], v[100:103], v[32:47]
	ds_read_b128 v[108:111], v171 offset:50432
	s_waitcnt lgkmcnt(0)
	v_mfma_f32_32x32x16_bf16 v[16:31], v[108:111], v[100:103], v[16:31]
	ds_read_b128 v[108:111], v191 offset:256
	s_waitcnt lgkmcnt(0)
	v_mfma_f32_32x32x16_bf16 v[0:15], v[108:111], v[100:103], v[0:15]
	ds_read_b128 v[100:103], v171 offset:288
	s_waitcnt lgkmcnt(0)
	v_mfma_f32_32x32x16_bf16 v[48:63], v[100:103], v[104:107], v[48:63]
	ds_read_b128 v[100:103], v171 offset:25376
	s_waitcnt lgkmcnt(0)
	v_mfma_f32_32x32x16_bf16 v[32:47], v[100:103], v[104:107], v[32:47]
	ds_read_b128 v[100:103], v171 offset:50464
	s_waitcnt lgkmcnt(0)
	v_mfma_f32_32x32x16_bf16 v[16:31], v[100:103], v[104:107], v[16:31]
	ds_read_b128 v[100:103], v191 offset:288
	s_waitcnt lgkmcnt(0)
	v_mfma_f32_32x32x16_bf16 v[0:15], v[100:103], v[104:107], v[0:15]
	v_add_u32_e32 v93, v93, v157
	v_cvt_f32_i32_e32 v93, v93
	v_rcp_f32_e32 v140, v117
	v_ashrrev_i32_e32 v113, 31, v112
	s_ashr_i32 s47, s46, 31
	v_fma_f32 v92, -v92, v93, v115
	v_log_f32_e32 v93, v117
	s_and_b64 vcc, exec, s[44:45]
	v_add_f32_e32 v100, v92, v93
	v_lshlrev_b64 v[92:93], 6, v[112:113]
	v_lshl_add_u64 v[92:93], s[22:23], 0, v[92:93]
	v_lshl_add_u64 v[92:93], s[46:47], 2, v[92:93]
	s_cbranch_vccnz .LBB0_1201
	v_max_f32_e32 v102, v100, v100
	s_waitcnt vmcnt(0)
	v_mov_b32_e32 v101, v252
	v_max_f32_e32 v103, v101, v101
	v_max_f32_e32 v104, v103, v102
	v_sub_f32_e32 v101, v101, v104
	v_sub_f32_e32 v102, v100, v104
	v_exp_f32_e32 v100, v101
	v_exp_f32_e32 v103, v102
	s_nop 0
	v_add_f32_e32 v101, v100, v103
	v_rcp_f32_e32 v102, v101
	v_log_f32_e32 v105, v101
	v_mov_b32_e32 v101, v140
	v_mul_f32_e32 v103, v103, v102
	v_pk_mul_f32 v[144:145], v[100:101], v[102:103]
	v_add_f32_e32 v100, v104, v105
	v_mov_b32_e32 v140, v145
	s_and_saveexec_b64 s[12:13], s[26:27]
	s_cbranch_execz .LBB0_1180
